# workgroup role index = blockIdx (no XCD-contiguous remap): the 64 WKV-scan workgroups spread over all 8 XCDs instead of filling two
# speedup vs baseline: 1.0106x; 1.0020x over previous
_Z3fwd4Args:
	s_load_dword s96, s[0:1], 0x148
	s_add_u32 s4, s0, 0x148
	s_addc_u32 s5, s1, 0
	s_mov_b32 s56, s2
	v_writelane_b32 v250, s4, 0
	s_waitcnt lgkmcnt(0)
	s_and_b32 s3, s96, 7
	s_cmp_lg_u32 s3, 0
	v_writelane_b32 v250, s5, 1
	v_writelane_b32 v250, s2, 2
	s_branch .LBB0_2
	v_readlane_b32 s5, v250, 2
	s_ashr_i32 s3, s5, 31
	s_lshr_b32 s3, s3, 29
	s_add_i32 s3, s5, s3
	s_and_b32 s4, s3, -8
	s_ashr_i32 s2, s96, 3
	s_sub_i32 s4, s5, s4
	s_mul_i32 s2, s2, s4
	s_ashr_i32 s3, s3, 3
	s_add_i32 s56, s2, s3
